# memory-K/V projection GEMM units placed on workgroups that carry one FFN1-up unit fewer (phase ends one unit earlier)
# speedup vs baseline: 1.0863x; 1.0012x over previous
;     __device__ void init(int K_, int G_, int c_) { P.init(NP, 2048, G_, c_); P.kt = K_ / BK; G = G_; c = c_; K = K_; }
;     __device__ bool next(int i, Unit& u) const {
;         const long L = (long)i * G + c; if (L >= nwg) return false;
;         int wgid = (int)L; { const int q = nwg / NXCD, r = nwg % NXCD, xcd = wgid % NXCD, off = wgid / NXCD; wgid = (xcd < r ? xcd * (q + 1) : r * (q + 1) + (xcd - r) * q) + off; }
;         const int nig = WGM * nN, gid = wgid / nig, fm = gid * WGM, gsz = (nM - fm) < WGM ? (nM - fm) : WGM;
;         u.pm = fm + ((wgid % nig) % gsz); u.pn = (wgid % nig) / gsz; u.nt = kt; u.ks = -1; u.koff = 0; return true;
; __global__ void __launch_bounds__(512, 2) fwd_mega(Args A) {
;     ...
;         pg8::Gemm g2{(const h16*)(ws + WS_MEMH), (const h16*)(ws + WS_WMKV), 512, 1024, DM}; S.init(512, 1024, G, blockIdx.x); S.kt = DM / 64;
;         pg8::gemm_phase(wv, lds, g2, S, pg8::EpiMemKV{A.out, (h16*)(ws + WS_MK16), (h16*)(ws + WS_MVT)});
.LBB0_191:
	s_sub_i32 s98, s2, 88
	s_cmp_lt_i32 s98, 0
	s_cselect_b32 s32, 0x100, 0
	s_add_i32 s98, s98, s32
	v_mov_b32_e32 v8, v170
	s_cmp_lt_i32 s98, 8
	s_cselect_b64 s[8:9], -1, 0
	s_cmp_gt_i32 s98, 7
	v_readfirstlane_b32 s18, v8
	s_cbranch_scc1 .LBB0_193
	s_ashr_i32 s0, s98, 31
	s_lshr_b32 s0, s0, 29
	s_add_i32 s0, s98, s0
	s_ashr_i32 s1, s0, 3
	s_and_b32 s0, s0, -8
	s_sub_i32 s0, s98, s0
	s_lshr_b32 s3, s0, 31
	s_lshl_b32 s0, s0, s3
	s_add_i32 s0, s0, s1
	s_ashr_i32 s1, s0, 31
	s_lshr_b32 s1, s1, 27
	s_add_i32 s1, s0, s1
	s_ashr_i32 s1, s1, 5
	s_lshl_b32 s3, s1, 3
	s_sub_i32 s4, 2, s3
	s_lshl_b32 s1, s1, 5
	s_min_u32 s4, s4, 8
	s_sub_i32 s5, s0, s1
	s_sext_i32_i8 s0, s5
	v_cvt_f32_ubyte0_e32 v1, s4
	v_cvt_f32_i32_e32 v0, s0
	v_rcp_iflag_f32_e32 v2, v1
	s_ashr_i32 s0, s0, 30
	s_or_b32 s6, s0, 1
	v_mul_f32_e32 v2, v0, v2
	v_trunc_f32_e32 v2, v2
	v_fma_f32 v0, -v2, v1, v0
	v_cvt_i32_f32_e32 v2, v2
	v_cmp_ge_f32_e64 s[0:1], |v0|, v1
	s_and_b64 s[0:1], s[0:1], exec
	s_cselect_b32 s0, s6, 0
	v_readfirstlane_b32 s1, v2
	s_add_i32 s0, s1, s0
	s_sext_i32_i8 s6, s0
	s_mul_i32 s0, s0, s4
	s_sub_i32 s0, s5, s0
	s_sext_i32_i8 s0, s0
	s_add_i32 s36, s3, s0

; __device__ __forceinline__ int opaque_tid(int wv) { int t = wv * 64 + (int)__builtin_amdgcn_mbcnt_hi(~0u, __builtin_amdgcn_mbcnt_lo(~0u, 0u)); asm volatile("" : "+v"(t)); return t; }
; #define PG8_STAGE(bufoff, gbase, voff) do { _Pragma("unroll") for (int _i = 0; _i < 2; ++_i) \
;         __builtin_amdgcn_global_load_lds((const unsigned*)((const char*)(gbase) + (voff)[_i]), (LAS unsigned*)(lds + (bufoff) + ldsw + _i * 8192), 16, 0, 0); } while (0)
; #define PG8_WAIT_V(n) asm volatile("s_waitcnt vmcnt(" #n ")" ::: "memory")
; template <class Epi, class Order>
; __device__ __forceinline__ void gemm_phase(int wv, LAS unsigned char* lds, const Gemm g, const Order& S, const Epi& E) {
;     const int tid = opaque_tid(wv), wid = __builtin_amdgcn_readfirstlane(tid >> 6), lane = tid & 63, wr = wid >> 2, wc = wid & 3, fr = lane & 15, fq = lane >> 4;
;     const int K = g.K;
;     unsigned voffA[2], voffB[2];
; #pragma unroll
;     for (int i = 0; i < 2; ++i) { int R, C; stage_rc(tid * 16 + i * 8192, R, C); const int Rb = (R & ~31) + perm32(R & 31);
;         voffA[i] = (unsigned)(R * K + C) * 2u; voffB[i] = (unsigned)(Rb * K + C) * 2u; }
;     const size_t kstep = (size_t)(BK * 2);
;     const size_t hstep = (size_t)HALF * K * 2;
;     const size_t tstep = 2 * hstep;
;     const unsigned ldsw = (unsigned)wid * 1024u;
;     const int aoff = lds_byte(wr * 64 + fr, fq * 8), boff = lds_byte(wc * 32 + fr, fq * 8);
;     ...
;     Unit cur, nxt; int ui = 0;
;     if (!S.next(0, cur)) return;
;     f32x4 acc[2][2][4][2];
; #pragma unroll
;     for (int a = 0; a < 2; ++a)
; #pragma unroll
;         for (int b = 0; b < 2; ++b)
; #pragma unroll
;             for (int m = 0; m < 4; ++m)
; #pragma unroll
;                 for (int n = 0; n < 2; ++n) acc[a][b][m][n] = (f32x4){0.f, 0.f, 0.f, 0.f};
;     h16x8 At[4][2], B0[2][2], B1[2][2];
;     const char* cA = (const char*)g.A + (size_t)cur.pm * tstep + cur.koff; const char* cB = (const char*)g.Bt + (size_t)cur.pn * tstep + cur.koff;
;     PG8_STAGE(PG8_SB(0, 0), cB, voffB); PG8_STAGE(PG8_SB(0, 1), cB + hstep, voffB); PG8_STAGE(PG8_SA(0, 0), cA, voffA); PG8_STAGE(PG8_SA(0, 1), cA + hstep, voffA);
;     if (wr == 1) PG8_BAR;
;     PG8_WAIT_V(2); PG8_BAR;
;     PG8_STAGE(PG8_SB(1, 0), cB + kstep, voffB); PG8_STAGE(PG8_SA(1, 0), cA + kstep, voffA); PG8_STAGE(PG8_SB(1, 1), cB + hstep + kstep, voffB);
;     PG8_WAIT_V(6); PG8_BAR;
.LBB0_196:
	s_add_u32 s10, s44, 0x3cc4d000
	s_addc_u32 s11, s45, 0
	s_add_u32 s14, s44, 0x3cccd000
	s_addc_u32 s15, s45, 0
	s_lshl_b32 s53, s16, 6
	s_lshl_b32 s7, s16, 13
	s_lshl_b32 s16, s17, 5
	s_and_b32 s24, s16, 0x60
	s_mov_b64 s[16:17], 0x80
	s_add_i32 m0, s33, 0x18000
	v_lshl_add_u64 v[6:7], v[6:7], 0, s[16:17]
	s_lshl_b32 s19, s24, 7
	s_waitcnt vmcnt(2)
	s_barrier
	global_load_lds_dwordx4 v[6:7], off
	v_lshl_add_u64 v[4:5], v[4:5], 0, s[16:17]
	s_add_i32 m0, s33, 0x1a000
	s_add_i32 s58, s33, 0x8000
	s_add_i32 s59, s33, 0xa000
	global_load_lds_dwordx4 v[4:5], off
	v_lshl_add_u64 v[0:1], v[0:1], 0, s[16:17]
	s_mov_b32 m0, s58
	s_add_u32 s20, s40, 0x80080
	global_load_lds_dwordx4 v[0:1], off
	v_lshl_add_u64 v[0:1], v[2:3], 0, s[16:17]
	s_mov_b32 m0, s59
	s_addc_u32 s21, s41, 0
	global_load_lds_dwordx4 v[0:1], off
	s_add_i32 m0, s33, 0x1c000
	v_lshl_add_u64 v[0:1], s[20:21], 0, v[130:131]
	global_load_lds_dwordx4 v[0:1], off
	v_lshl_add_u64 v[0:1], s[20:21], 0, v[134:135]
	s_add_i32 m0, s33, 0x1e000
	v_and_b32_e32 v157, 15, v8
	global_load_lds_dwordx4 v[0:1], off
	v_lshrrev_b32_e32 v0, 1, v8
	v_and_b32_e32 v0, 24, v0
	v_lshlrev_b32_e32 v1, 1, v0
	v_lshlrev_b32_e32 v2, 2, v8
	v_or_b32_e32 v159, s24, v0
	v_lshlrev_b32_e32 v0, 15, v9
	v_lshl_or_b32 v1, v157, 6, v1
	v_and_b32_e32 v2, 32, v2
	v_and_b32_e32 v0, 0xffff0000, v0
	v_bitop3_b32 v3, v1, s7, v2 bitop3:0xde
	v_bitop3_b32 v158, v1, s19, v2 bitop3:0xde
	s_cmpk_lt_u32 s18, 0x100
	v_lshl_add_u32 v0, v10, 12, v0
	v_and_b32_e32 v1, 1, v9
	s_cselect_b64 s[18:19], -1, 0
	s_ashr_i32 s64, s98, 31
	v_lshl_or_b32 v0, v1, 6, v0
	s_waitcnt lgkmcnt(0)
	s_add_u32 s20, s62, 0x14e00000
	v_lshl_add_u32 v138, v11, 1, v0
	v_lshlrev_b32_e32 v0, 15, v12
	s_addc_u32 s21, s63, 0
	v_and_b32_e32 v0, 0xffff0000, v0
	s_waitcnt vmcnt(6)
	s_add_u32 s22, s62, 0x14d00000
	v_lshl_add_u32 v0, v13, 12, v0
	v_and_b32_e32 v1, 1, v12
	s_addc_u32 s23, s63, 0
	v_lshl_or_b32 v0, v1, 6, v0
	s_add_i32 s65, 0, 0x10000
	s_add_i32 s66, 0, 0x14000
	v_mov_b32_e32 v139, v137
	v_lshl_add_u32 v140, v14, 1, v0
	v_mov_b32_e32 v141, v137
	v_add_u32_e32 v160, s65, v158
	v_add_u32_e32 v161, s66, v158
	v_add_u32_e32 v162, 0, v3
	s_movk_i32 s67, 0x1ff
	s_movk_i32 s68, 0xdf
	s_movk_i32 s69, 0xef
	s_movk_i32 s70, 0xff
	v_mov_b32_e32 v163, 0x78
	v_mov_b32_e32 v164, 0xcf
	s_barrier
	s_branch .LBB0_199

;     __device__ bool next(int i, Unit& u) const {
;         const long L = (long)i * G + c; if (L >= nwg) return false;
;         int wgid = (int)L; { const int q = nwg / NXCD, r = nwg % NXCD, xcd = wgid % NXCD, off = wgid / NXCD; wgid = (xcd < r ? xcd * (q + 1) : r * (q + 1) + (xcd - r) * q) + off; }
;         const int nig = WGM * nN, gid = wgid / nig, fm = gid * WGM, gsz = (nM - fm) < WGM ? (nM - fm) : WGM;
;         u.pm = fm + ((wgid % nig) % gsz); u.pn = (wgid % nig) / gsz; u.nt = kt; u.ks = -1; u.koff = 0; return true;
; template <class Epi, class Order>
; __device__ __forceinline__ void gemm_phase(int wv, LAS unsigned char* lds, const Gemm g, const Order& S, const Epi& E) {
;     ...
;         const bool has_next = S.next(ui + 1, nxt);
;         const char* nA = has_next ? (const char*)g.A + (size_t)nxt.pm * tstep + nxt.koff : cA; const char* nB = has_next ? (const char*)g.Bt + (size_t)nxt.pn * tstep + nxt.koff : cB;
.LBB0_199:
	s_add_i32 s51, s51, 1
	s_mul_i32 s7, s51, s55
	s_mul_hi_u32 s25, s51, s54
	s_add_i32 s25, s25, s7
	s_mul_i32 s7, s51, s54
	s_add_u32 s30, s7, s98
	s_addc_u32 s31, s25, s64
	v_cmp_gt_i64_e64 s[34:35], s[30:31], 7
	v_cmp_lt_i64_e64 s[28:29], s[30:31], 8
	s_and_b64 vcc, exec, s[34:35]
	s_cbranch_vccnz .LBB0_201
	s_ashr_i32 s7, s30, 31
	s_lshr_b32 s7, s7, 29
	s_add_i32 s7, s30, s7
	s_ashr_i32 s24, s7, 3
	s_and_b32 s7, s7, -8
	s_sub_i32 s7, s30, s7
	s_lshr_b32 s25, s7, 31
	s_lshl_b32 s7, s7, s25
	s_add_i32 s7, s7, s24
	s_ashr_i32 s24, s7, 31
	s_lshr_b32 s24, s24, 27
	s_add_i32 s24, s7, s24
	s_ashr_i32 s25, s24, 5
	s_lshl_b32 s25, s25, 3
	s_sub_i32 s26, 2, s25
	s_min_i32 s26, s26, 8
	s_abs_i32 s27, s26
	v_cvt_f32_u32_e32 v0, s27
	s_sub_i32 s31, 0, s27
	s_andn2_b32 s24, s24, 31
	s_sub_i32 s7, s7, s24
	v_rcp_iflag_f32_e32 v0, v0
	s_abs_i32 s24, s7
	s_xor_b32 s30, s7, s26
	s_ashr_i32 s30, s30, 31
	v_mul_f32_e32 v0, 0x4f7ffffe, v0
	v_cvt_u32_f32_e32 v0, v0
	s_nop 0
	v_readfirstlane_b32 s34, v0
	s_mul_i32 s31, s31, s34
	s_mul_hi_u32 s31, s34, s31
	s_add_i32 s34, s34, s31
	s_mul_hi_u32 s31, s24, s34
	s_mul_i32 s34, s31, s27
	s_sub_i32 s24, s24, s34
	s_add_i32 s35, s31, 1
	s_sub_i32 s34, s24, s27
	s_cmp_ge_u32 s24, s27
	s_cselect_b32 s31, s35, s31
	s_cselect_b32 s24, s34, s24
	s_add_i32 s34, s31, 1
	s_cmp_ge_u32 s24, s27
	s_cselect_b32 s24, s34, s31
	s_xor_b32 s24, s24, s30
	s_sub_i32 s24, s24, s30
	s_mul_i32 s26, s24, s26
	s_sub_i32 s7, s7, s26
	s_add_i32 s26, s7, s25
